# v27: v26 + int8 GEMM output stored as full 128-byte lines (adjacent column blocks per wave, DPP lane exchange)
# speedup vs baseline: 1.0052x; 1.0000x over previous
.LBB0_309:
	s_add_u32 s26, s48, 0xfffc0080
	s_addc_u32 s27, s49, -1
	s_add_i32 s68, 0, 0x10000
	s_cmp_eq_u32 s67, 12
	s_cselect_b32 s53, s19, s27
	s_cselect_b32 s52, s63, s26
	s_cselect_b32 s51, s17, s66
	s_cselect_b32 s50, s64, s65
	s_add_i32 s69, 0, 0x14000
	ds_read_b128 v[56:59], v224
	ds_read_b128 v[60:63], v224 offset:1024
	ds_read_b128 v[68:71], v224 offset:2048
	ds_read_b128 v[72:75], v224 offset:3072
	ds_read_b128 v[158:161], v225
	ds_read_b128 v[162:165], v225 offset:1024
	ds_read_b128 v[170:173], v225 offset:2048
	ds_read_b128 v[174:177], v225 offset:3072
	s_add_i32 m0, s35, 0xc000
	ds_read_b128 v[178:181], v169
	ds_read_b128 v[182:185], v169 offset:1024
	ds_read_b128 v[186:189], v169 offset:2048
	ds_read_b128 v[190:193], v169 offset:3072
	ds_read_b128 v[198:201], v169 offset:4096
	ds_read_b128 v[202:205], v169 offset:5120
	ds_read_b128 v[206:209], v169 offset:6144
	ds_read_b128 v[210:213], v169 offset:7168
	global_load_lds_dwordx4 v154, s[48:49]
	s_add_i32 m0, s35, 0xe000
	s_nop 0
	global_load_lds_dwordx4 v156, s[48:49]
	s_waitcnt vmcnt(8)
	s_waitcnt lgkmcnt(0)
	s_barrier
	s_setprio 1
	s_waitcnt lgkmcnt(0)
	v_mfma_i32_16x16x64_i8 v[142:145], v[56:59], v[178:181], v[142:145]
	v_mfma_i32_16x16x64_i8 v[138:141], v[68:71], v[178:181], v[138:141]
	v_mfma_i32_16x16x64_i8 v[126:129], v[56:59], v[186:189], v[126:129]
	v_mfma_i32_16x16x64_i8 v[122:125], v[68:71], v[186:189], v[122:125]
	v_mfma_i32_16x16x64_i8 v[110:113], v[56:59], v[198:201], v[110:113]
	v_mfma_i32_16x16x64_i8 v[106:109], v[68:71], v[198:201], v[106:109]
	v_mfma_i32_16x16x64_i8 v[92:95], v[56:59], v[206:209], v[92:95]
	v_mfma_i32_16x16x64_i8 v[88:91], v[68:71], v[206:209], v[88:91]
	v_mfma_i32_16x16x64_i8 v[142:145], v[60:63], v[182:185], v[142:145]
	v_mfma_i32_16x16x64_i8 v[138:141], v[72:75], v[182:185], v[138:141]
	v_mfma_i32_16x16x64_i8 v[126:129], v[60:63], v[190:193], v[126:129]
	v_mfma_i32_16x16x64_i8 v[122:125], v[72:75], v[190:193], v[122:125]
	v_mfma_i32_16x16x64_i8 v[110:113], v[60:63], v[202:205], v[110:113]
	v_mfma_i32_16x16x64_i8 v[106:109], v[72:75], v[202:205], v[106:109]
	v_mfma_i32_16x16x64_i8 v[92:95], v[60:63], v[210:213], v[92:95]
	v_mfma_i32_16x16x64_i8 v[88:91], v[72:75], v[210:213], v[88:91]
	s_setprio 0
	s_setprio 1
	v_mfma_i32_16x16x64_i8 v[134:137], v[158:161], v[178:181], v[134:137]
	v_mfma_i32_16x16x64_i8 v[130:133], v[170:173], v[178:181], v[130:133]
	v_mfma_i32_16x16x64_i8 v[118:121], v[158:161], v[186:189], v[118:121]
	v_mfma_i32_16x16x64_i8 v[114:117], v[170:173], v[186:189], v[114:117]
	v_mfma_i32_16x16x64_i8 v[102:105], v[158:161], v[198:201], v[102:105]
	v_mfma_i32_16x16x64_i8 v[98:101], v[170:173], v[198:201], v[98:101]
	v_mfma_i32_16x16x64_i8 v[84:87], v[158:161], v[206:209], v[84:87]
	v_mfma_i32_16x16x64_i8 v[80:83], v[170:173], v[206:209], v[80:83]
	v_mfma_i32_16x16x64_i8 v[134:137], v[162:165], v[182:185], v[134:137]
	v_mfma_i32_16x16x64_i8 v[130:133], v[174:177], v[182:185], v[130:133]
	v_mfma_i32_16x16x64_i8 v[118:121], v[162:165], v[190:193], v[118:121]
	v_mfma_i32_16x16x64_i8 v[114:117], v[174:177], v[190:193], v[114:117]
	v_mfma_i32_16x16x64_i8 v[102:105], v[162:165], v[202:205], v[102:105]
	v_mfma_i32_16x16x64_i8 v[98:101], v[174:177], v[202:205], v[98:101]
	v_mfma_i32_16x16x64_i8 v[84:87], v[162:165], v[210:213], v[84:87]
	v_mfma_i32_16x16x64_i8 v[80:83], v[174:177], v[210:213], v[80:83]
	s_setprio 0
	s_barrier
	s_add_i32 s26, s68, s56
	s_mov_b32 m0, s26
	ds_read_b128 v[178:181], v169 offset:16384
	ds_read_b128 v[182:185], v169 offset:17408
	ds_read_b128 v[186:189], v169 offset:18432
	ds_read_b128 v[190:193], v169 offset:19456
	ds_read_b128 v[198:201], v169 offset:20480
	ds_read_b128 v[202:205], v169 offset:21504
	ds_read_b128 v[206:209], v169 offset:22528
	ds_read_b128 v[210:213], v169 offset:23552
	global_load_lds_dwordx4 v150, s[50:51]
	s_add_i32 m0, s26, 0x2000
	s_add_u32 s26, s50, 0x10000
	s_addc_u32 s27, s51, 0
	s_add_i32 s68, s69, s56
	global_load_lds_dwordx4 v146, s[50:51]
	s_mov_b32 m0, s68
	s_nop 0
	global_load_lds_dwordx4 v150, s[26:27]
	s_add_i32 m0, s68, 0x2000
	s_nop 0
	global_load_lds_dwordx4 v146, s[26:27]
	s_mov_b32 m0, s35
	s_nop 0
	global_load_lds_dwordx4 v152, s[52:53]
	s_mov_b32 m0, s57
	s_nop 0
	global_load_lds_dwordx4 v148, s[52:53]
	s_waitcnt vmcnt(8)
	s_waitcnt lgkmcnt(0)
	s_barrier
	s_setprio 1
	s_waitcnt lgkmcnt(0)
	v_mfma_i32_16x16x64_i8 v[76:79], v[56:59], v[178:181], v[76:79]
	v_mfma_i32_16x16x64_i8 v[64:67], v[68:71], v[178:181], v[64:67]
	v_mfma_i32_16x16x64_i8 v[44:47], v[56:59], v[186:189], v[44:47]
	v_mfma_i32_16x16x64_i8 v[40:43], v[68:71], v[186:189], v[40:43]
	v_mfma_i32_16x16x64_i8 v[28:31], v[56:59], v[198:201], v[28:31]
	v_mfma_i32_16x16x64_i8 v[24:27], v[68:71], v[198:201], v[24:27]
	v_mfma_i32_16x16x64_i8 v[12:15], v[56:59], v[206:209], v[12:15]
	v_mfma_i32_16x16x64_i8 v[8:11], v[68:71], v[206:209], v[8:11]
	v_mfma_i32_16x16x64_i8 v[76:79], v[60:63], v[182:185], v[76:79]
	v_mfma_i32_16x16x64_i8 v[64:67], v[72:75], v[182:185], v[64:67]
	v_mfma_i32_16x16x64_i8 v[44:47], v[60:63], v[190:193], v[44:47]
	v_mfma_i32_16x16x64_i8 v[40:43], v[72:75], v[190:193], v[40:43]
	v_mfma_i32_16x16x64_i8 v[28:31], v[60:63], v[202:205], v[28:31]
	v_mfma_i32_16x16x64_i8 v[24:27], v[72:75], v[202:205], v[24:27]
	v_mfma_i32_16x16x64_i8 v[12:15], v[60:63], v[210:213], v[12:15]
	v_mfma_i32_16x16x64_i8 v[8:11], v[72:75], v[210:213], v[8:11]
	s_setprio 0
	s_setprio 1
	v_mfma_i32_16x16x64_i8 v[52:55], v[158:161], v[178:181], v[52:55]
	v_mfma_i32_16x16x64_i8 v[48:51], v[170:173], v[178:181], v[48:51]
	v_mfma_i32_16x16x64_i8 v[36:39], v[158:161], v[186:189], v[36:39]
	v_mfma_i32_16x16x64_i8 v[32:35], v[170:173], v[186:189], v[32:35]
	v_mfma_i32_16x16x64_i8 v[20:23], v[158:161], v[198:201], v[20:23]
	v_mfma_i32_16x16x64_i8 v[16:19], v[170:173], v[198:201], v[16:19]
	v_mfma_i32_16x16x64_i8 v[4:7], v[158:161], v[206:209], v[4:7]
	v_mfma_i32_16x16x64_i8 v[0:3], v[170:173], v[206:209], v[0:3]
	v_mfma_i32_16x16x64_i8 v[52:55], v[162:165], v[182:185], v[52:55]
	v_mfma_i32_16x16x64_i8 v[48:51], v[174:177], v[182:185], v[48:51]
	v_mfma_i32_16x16x64_i8 v[36:39], v[162:165], v[190:193], v[36:39]
	v_mfma_i32_16x16x64_i8 v[32:35], v[174:177], v[190:193], v[32:35]
	v_mfma_i32_16x16x64_i8 v[20:23], v[162:165], v[202:205], v[20:23]
	v_mfma_i32_16x16x64_i8 v[16:19], v[174:177], v[202:205], v[16:19]
	v_mfma_i32_16x16x64_i8 v[4:7], v[162:165], v[210:213], v[4:7]
	v_mfma_i32_16x16x64_i8 v[0:3], v[174:177], v[210:213], v[0:3]
	s_setprio 0
	s_barrier
	s_add_i32 s68, 0, 0x18000
	s_add_i32 s69, 0, 0x1c000
	ds_read_b128 v[56:59], v226
	ds_read_b128 v[60:63], v226 offset:1024
	ds_read_b128 v[68:71], v226 offset:2048
	ds_read_b128 v[72:75], v226 offset:3072
	ds_read_b128 v[158:161], v227
	ds_read_b128 v[162:165], v227 offset:1024
	ds_read_b128 v[170:173], v227 offset:2048
	ds_read_b128 v[174:177], v227 offset:3072
	s_add_u32 s26, s52, 0x40000
	s_addc_u32 s27, s53, 0
	s_mov_b32 m0, s58
	ds_read_b128 v[178:181], v169 offset:32768
	ds_read_b128 v[182:185], v169 offset:33792
	ds_read_b128 v[186:189], v169 offset:34816
	ds_read_b128 v[190:193], v169 offset:35840
	ds_read_b128 v[198:201], v169 offset:36864
	ds_read_b128 v[202:205], v169 offset:37888
	ds_read_b128 v[206:209], v169 offset:38912
	ds_read_b128 v[210:213], v169 offset:39936
	global_load_lds_dwordx4 v152, s[26:27]
	s_mov_b32 m0, s59
	s_nop 0
	global_load_lds_dwordx4 v148, s[26:27]
	s_waitcnt vmcnt(8)
	s_waitcnt lgkmcnt(0)
	s_barrier
	s_setprio 1
	s_waitcnt lgkmcnt(0)
	v_mfma_i32_16x16x64_i8 v[142:145], v[56:59], v[178:181], v[142:145]
	v_mfma_i32_16x16x64_i8 v[138:141], v[68:71], v[178:181], v[138:141]
	v_mfma_i32_16x16x64_i8 v[126:129], v[56:59], v[186:189], v[126:129]
	v_mfma_i32_16x16x64_i8 v[122:125], v[68:71], v[186:189], v[122:125]
	v_mfma_i32_16x16x64_i8 v[110:113], v[56:59], v[198:201], v[110:113]
	v_mfma_i32_16x16x64_i8 v[106:109], v[68:71], v[198:201], v[106:109]
	v_mfma_i32_16x16x64_i8 v[92:95], v[56:59], v[206:209], v[92:95]
	v_mfma_i32_16x16x64_i8 v[88:91], v[68:71], v[206:209], v[88:91]
	v_mfma_i32_16x16x64_i8 v[142:145], v[60:63], v[182:185], v[142:145]
	v_mfma_i32_16x16x64_i8 v[138:141], v[72:75], v[182:185], v[138:141]
	v_mfma_i32_16x16x64_i8 v[126:129], v[60:63], v[190:193], v[126:129]
	v_mfma_i32_16x16x64_i8 v[122:125], v[72:75], v[190:193], v[122:125]
	v_mfma_i32_16x16x64_i8 v[110:113], v[60:63], v[202:205], v[110:113]
	v_mfma_i32_16x16x64_i8 v[106:109], v[72:75], v[202:205], v[106:109]
	v_mfma_i32_16x16x64_i8 v[92:95], v[60:63], v[210:213], v[92:95]
	v_mfma_i32_16x16x64_i8 v[88:91], v[72:75], v[210:213], v[88:91]
	s_setprio 0
	s_setprio 1
	v_mfma_i32_16x16x64_i8 v[134:137], v[158:161], v[178:181], v[134:137]
	v_mfma_i32_16x16x64_i8 v[130:133], v[170:173], v[178:181], v[130:133]
	v_mfma_i32_16x16x64_i8 v[118:121], v[158:161], v[186:189], v[118:121]
	v_mfma_i32_16x16x64_i8 v[114:117], v[170:173], v[186:189], v[114:117]
	v_mfma_i32_16x16x64_i8 v[102:105], v[158:161], v[198:201], v[102:105]
	v_mfma_i32_16x16x64_i8 v[98:101], v[170:173], v[198:201], v[98:101]
	v_mfma_i32_16x16x64_i8 v[84:87], v[158:161], v[206:209], v[84:87]
	v_mfma_i32_16x16x64_i8 v[80:83], v[170:173], v[206:209], v[80:83]
	v_mfma_i32_16x16x64_i8 v[134:137], v[162:165], v[182:185], v[134:137]
	v_mfma_i32_16x16x64_i8 v[130:133], v[174:177], v[182:185], v[130:133]
	v_mfma_i32_16x16x64_i8 v[118:121], v[162:165], v[190:193], v[118:121]
	v_mfma_i32_16x16x64_i8 v[114:117], v[174:177], v[190:193], v[114:117]
	v_mfma_i32_16x16x64_i8 v[102:105], v[162:165], v[202:205], v[102:105]
	v_mfma_i32_16x16x64_i8 v[98:101], v[174:177], v[202:205], v[98:101]
	v_mfma_i32_16x16x64_i8 v[84:87], v[162:165], v[210:213], v[84:87]
	v_mfma_i32_16x16x64_i8 v[80:83], v[174:177], v[210:213], v[80:83]
	s_setprio 0
	s_barrier
	s_add_i32 s26, s68, s56
	s_add_i32 m0, s26, 0xffffff80
	ds_read_b128 v[178:181], v169 offset:49152
	ds_read_b128 v[182:185], v169 offset:50176
	ds_read_b128 v[186:189], v169 offset:51200
	ds_read_b128 v[190:193], v169 offset:52224
	ds_read_b128 v[198:201], v169 offset:53248
	ds_read_b128 v[202:205], v169 offset:54272
	ds_read_b128 v[206:209], v169 offset:55296
	ds_read_b128 v[210:213], v169 offset:56320
	global_load_lds_dwordx4 v150, s[50:51] offset:128
	s_add_i32 m0, s26, 0x1f80
	s_add_u32 s26, s50, 0x10080
	s_addc_u32 s27, s51, 0
	s_add_i32 s100, s69, s56
	global_load_lds_dwordx4 v146, s[50:51] offset:128
	s_mov_b32 m0, s100
	s_nop 0
	global_load_lds_dwordx4 v150, s[26:27]
	s_add_i32 m0, s100, 0x2000
	s_nop 0
	global_load_lds_dwordx4 v146, s[26:27]
	s_add_i32 m0, s4, 0xffffff80
	s_nop 0
	global_load_lds_dwordx4 v152, s[52:53] offset:128
	s_add_i32 m0, s60, 0xffffff80
	s_nop 0
	global_load_lds_dwordx4 v148, s[52:53] offset:128
	s_waitcnt vmcnt(8)
	s_waitcnt lgkmcnt(0)
	s_barrier
	s_setprio 1
	s_waitcnt lgkmcnt(0)
	v_mfma_i32_16x16x64_i8 v[76:79], v[56:59], v[178:181], v[76:79]
	v_mfma_i32_16x16x64_i8 v[64:67], v[68:71], v[178:181], v[64:67]
	v_mfma_i32_16x16x64_i8 v[44:47], v[56:59], v[186:189], v[44:47]
	v_mfma_i32_16x16x64_i8 v[40:43], v[68:71], v[186:189], v[40:43]
	v_mfma_i32_16x16x64_i8 v[28:31], v[56:59], v[198:201], v[28:31]
	v_mfma_i32_16x16x64_i8 v[24:27], v[68:71], v[198:201], v[24:27]
	v_mfma_i32_16x16x64_i8 v[12:15], v[56:59], v[206:209], v[12:15]
	v_mfma_i32_16x16x64_i8 v[8:11], v[68:71], v[206:209], v[8:11]
	v_mfma_i32_16x16x64_i8 v[76:79], v[60:63], v[182:185], v[76:79]
	v_mfma_i32_16x16x64_i8 v[64:67], v[72:75], v[182:185], v[64:67]
	v_mfma_i32_16x16x64_i8 v[44:47], v[60:63], v[190:193], v[44:47]
	v_mfma_i32_16x16x64_i8 v[40:43], v[72:75], v[190:193], v[40:43]
	v_mfma_i32_16x16x64_i8 v[28:31], v[60:63], v[202:205], v[28:31]
	v_mfma_i32_16x16x64_i8 v[24:27], v[72:75], v[202:205], v[24:27]
	v_mfma_i32_16x16x64_i8 v[12:15], v[60:63], v[210:213], v[12:15]
	v_mfma_i32_16x16x64_i8 v[8:11], v[72:75], v[210:213], v[8:11]
	s_setprio 0
	s_setprio 1
	v_mfma_i32_16x16x64_i8 v[52:55], v[158:161], v[178:181], v[52:55]
	v_mfma_i32_16x16x64_i8 v[48:51], v[170:173], v[178:181], v[48:51]
	v_mfma_i32_16x16x64_i8 v[36:39], v[158:161], v[186:189], v[36:39]
	v_mfma_i32_16x16x64_i8 v[32:35], v[170:173], v[186:189], v[32:35]
	v_mfma_i32_16x16x64_i8 v[20:23], v[158:161], v[198:201], v[20:23]
	v_mfma_i32_16x16x64_i8 v[16:19], v[170:173], v[198:201], v[16:19]
	v_mfma_i32_16x16x64_i8 v[4:7], v[158:161], v[206:209], v[4:7]
	v_mfma_i32_16x16x64_i8 v[0:3], v[170:173], v[206:209], v[0:3]
	v_mfma_i32_16x16x64_i8 v[52:55], v[162:165], v[182:185], v[52:55]
	v_mfma_i32_16x16x64_i8 v[48:51], v[174:177], v[182:185], v[48:51]
	v_mfma_i32_16x16x64_i8 v[36:39], v[162:165], v[190:193], v[36:39]
	v_mfma_i32_16x16x64_i8 v[32:35], v[174:177], v[190:193], v[32:35]
	v_mfma_i32_16x16x64_i8 v[20:23], v[162:165], v[202:205], v[20:23]
	v_mfma_i32_16x16x64_i8 v[16:19], v[174:177], v[202:205], v[16:19]
	v_mfma_i32_16x16x64_i8 v[4:7], v[162:165], v[210:213], v[4:7]
	v_mfma_i32_16x16x64_i8 v[0:3], v[174:177], v[210:213], v[0:3]
	s_setprio 0
	s_barrier
	s_add_i32 s67, s67, 2
	s_add_u32 s48, s48, 0x100
	s_addc_u32 s49, s49, 0
	s_add_u32 s65, s65, 0x100
	s_addc_u32 s66, s66, 0
	s_cmp_gt_u32 s67, 13
	s_cbranch_scc0 .LBB0_309
	s_and_b64 vcc, exec, s[14:15]
	s_cbranch_vccz .LBB0_312
	s_barrier
